# compressed-branch importance blocks: 8 lane rotations (+4 partial reads) issued together, one LDS wait per block
# baseline (speedup 1.0000x reference)
; DI float lane_get(float v, int srclane) { return __int_as_float(__builtin_amdgcn_ds_bpermute(srclane << 2, __float_as_int(v))); }
; #define LAS __attribute__((address_space(3)))
; DI float red4_sum(float v, int lane) { v += lane_get(v, lane ^ 16); v += lane_get(v, lane ^ 32); return v; }
; DI void attn_phase(const Params& p, const int layer, const int wid_s) {
;     ...
;         ps = red4_sum(ps, lane);
;         const float inv = ps > 0.f ? 1.f / ps : 0.f;
; #pragma unroll
;         for (int nt = 0; nt < 8; ++nt) s[nt] = s[nt] * inv;
;         if (cur >= 8)
; #pragma unroll
;         for (int nt = 0; nt < 8; ++nt) {
;           const float x1 = lane_get(s[nt][3], (lane - 16) & 63);
;           const float x2 = nt > 0 ? lane_get(s[nt > 0 ? nt - 1 : 0][3], (lane - 16) & 63) : 0.f;
;           const float left = fq > 0 ? x1 : x2;
;           const float im = left + 2.f * (s[nt][0] + s[nt][1] + s[nt][2]) + s[nt][3];
;           LAS float* ip = impx + (wave * 8 + nt) * 64;
;           if (hp == 0) *ip = im; else *ip += im;
.LBB0_264:
	ds_bpermute_b32 v0, v179, v5
	s_cmp_gt_i32 s54, 7
	v_add_u32_e32 v151, s64, v177
	s_cselect_b64 s[12:13], -1, 0
	s_cmp_lt_i32 s54, 8
	s_waitcnt lgkmcnt(0)
	v_add_f32_e32 v0, v5, v0
	ds_bpermute_b32 v5, v180, v0
	v_add_u32_e32 v155, 0x80, v151
	s_waitcnt lgkmcnt(0)
	v_add_f32_e32 v0, v0, v5
	v_div_scale_f32 v5, s[14:15], v0, v0, 1.0
	v_rcp_f32_e32 v114, v5
	v_div_scale_f32 v115, vcc, 1.0, v0, 1.0
	v_fma_f32 v116, -v5, v114, 1.0
	v_fmac_f32_e32 v114, v116, v114
	v_mul_f32_e32 v116, v115, v114
	v_fma_f32 v117, -v5, v116, v115
	v_fmac_f32_e32 v116, v117, v114
	v_fma_f32 v5, -v5, v116, v115
	v_div_fmas_f32 v5, v5, v114, v116
	v_div_fixup_f32 v5, v5, v0, 1.0
	v_cmp_lt_f32_e32 vcc, 0, v0
	s_nop 1
	v_cndmask_b32_e32 v0, 0, v5, vcc
	v_pk_mul_f32 v[134:135], v[124:125], v[0:1] op_sel_hi:[1,0]
	v_pk_mul_f32 v[152:153], v[6:7], v[0:1] op_sel_hi:[1,0]
	v_pk_mul_f32 v[88:89], v[88:89], v[0:1] op_sel_hi:[1,0]
	v_pk_mul_f32 v[2:3], v[2:3], v[0:1] op_sel_hi:[1,0]
	v_pk_mul_f32 v[126:127], v[94:95], v[0:1] op_sel_hi:[1,0]
	v_pk_mul_f32 v[128:129], v[92:93], v[0:1] op_sel_hi:[1,0]
	v_pk_mul_f32 v[130:131], v[96:97], v[0:1] op_sel_hi:[1,0]
	v_pk_mul_f32 v[132:133], v[90:91], v[0:1] op_sel_hi:[1,0]
	v_pk_mul_f32 v[114:115], v[102:103], v[0:1] op_sel_hi:[1,0]
	v_pk_mul_f32 v[116:117], v[100:101], v[0:1] op_sel_hi:[1,0]
	v_pk_mul_f32 v[118:119], v[104:105], v[0:1] op_sel_hi:[1,0]
	v_pk_mul_f32 v[124:125], v[98:99], v[0:1] op_sel_hi:[1,0]
	v_pk_mul_f32 v[6:7], v[110:111], v[0:1] op_sel_hi:[1,0]
	v_pk_mul_f32 v[108:109], v[108:109], v[0:1] op_sel_hi:[1,0]
	v_pk_mul_f32 v[110:111], v[112:113], v[0:1] op_sel_hi:[1,0]
	v_pk_mul_f32 v[112:113], v[106:107], v[0:1] op_sel_hi:[1,0]
	s_cbranch_scc1 .LBB0_266
	ds_bpermute_b32 v198, v181, v135
	ds_bpermute_b32 v199, v181, v89
	ds_bpermute_b32 v200, v181, v127
	ds_bpermute_b32 v201, v181, v131
	ds_bpermute_b32 v202, v181, v115
	ds_bpermute_b32 v203, v181, v119
	ds_bpermute_b32 v204, v181, v7
	ds_bpermute_b32 v205, v181, v111
	s_waitcnt lgkmcnt(0)
	v_add_f32_e32 v5, v152, v153
	v_add_f32_e32 v5, v134, v5
	v_add_f32_e32 v91, v2, v3
	v_add_f32_e32 v91, v88, v91
	v_cndmask_b32_e64 v92, v198, 0, s[62:63]
	v_fmac_f32_e32 v92, 2.0, v5
	v_add_f32_e32 v5, v135, v92
	v_cndmask_b32_e64 v0, v199, v198, s[62:63]
	v_fmac_f32_e32 v0, 2.0, v91
	v_add_f32_e32 v0, v89, v0
	ds_write2st64_b32 v155, v5, v0 offset0:88 offset1:89
	v_add_f32_e32 v5, v128, v129
	v_add_f32_e32 v5, v126, v5
	v_add_f32_e32 v91, v132, v133
	v_add_f32_e32 v91, v130, v91
	v_cndmask_b32_e64 v92, v200, v199, s[62:63]
	v_fmac_f32_e32 v92, 2.0, v5
	v_add_f32_e32 v5, v127, v92
	v_cndmask_b32_e64 v0, v201, v200, s[62:63]
	v_fmac_f32_e32 v0, 2.0, v91
	v_add_f32_e32 v0, v131, v0
	ds_write2st64_b32 v155, v5, v0 offset0:90 offset1:91
	v_add_f32_e32 v5, v116, v117
	v_add_f32_e32 v5, v114, v5
	v_add_f32_e32 v91, v124, v125
	v_add_f32_e32 v91, v118, v91
	v_cndmask_b32_e64 v92, v202, v201, s[62:63]
	v_fmac_f32_e32 v92, 2.0, v5
	v_add_f32_e32 v5, v115, v92
	v_cndmask_b32_e64 v0, v203, v202, s[62:63]
	v_fmac_f32_e32 v0, 2.0, v91
	v_add_f32_e32 v0, v119, v0
	ds_write2st64_b32 v155, v5, v0 offset0:92 offset1:93
	v_add_f32_e32 v5, v108, v109
	v_add_f32_e32 v5, v6, v5
	v_add_f32_e32 v91, v112, v113
	v_add_f32_e32 v91, v110, v91
	v_cndmask_b32_e64 v92, v204, v203, s[62:63]
	v_fmac_f32_e32 v92, 2.0, v5
	v_add_f32_e32 v5, v7, v92
	v_cndmask_b32_e64 v0, v205, v204, s[62:63]
	v_fmac_f32_e32 v0, 2.0, v91
	v_add_f32_e32 v0, v111, v0
	ds_write2st64_b32 v155, v5, v0 offset0:94 offset1:95

; DI float lane_get(float v, int srclane) { return __int_as_float(__builtin_amdgcn_ds_bpermute(srclane << 2, __float_as_int(v))); }
; #define LAS __attribute__((address_space(3)))
; DI float red4_sum(float v, int lane) { v += lane_get(v, lane ^ 16); v += lane_get(v, lane ^ 32); return v; }
; DI void attn_phase(const Params& p, const int layer, const int wid_s) {
;     ...
;         ps = red4_sum(ps, lane);
;         const float inv = ps > 0.f ? 1.f / ps : 0.f;
; #pragma unroll
;         for (int nt = 0; nt < 8; ++nt) s[nt] = s[nt] * inv;
;         if (cur >= 8)
; #pragma unroll
;         for (int nt = 0; nt < 8; ++nt) {
;           const float x1 = lane_get(s[nt][3], (lane - 16) & 63);
;           const float x2 = nt > 0 ? lane_get(s[nt > 0 ? nt - 1 : 0][3], (lane - 16) & 63) : 0.f;
;           const float left = fq > 0 ? x1 : x2;
;           const float im = left + 2.f * (s[nt][0] + s[nt][1] + s[nt][2]) + s[nt][3];
;           LAS float* ip = impx + (wave * 8 + nt) * 64;
;           if (hp == 0) *ip = im; else *ip += im;
.LBB0_324:
	ds_bpermute_b32 v0, v179, v5
	s_waitcnt lgkmcnt(0)
	v_add_f32_e32 v0, v5, v0
	ds_bpermute_b32 v5, v180, v0
	s_waitcnt lgkmcnt(0)
	v_add_f32_e32 v0, v0, v5
	v_div_scale_f32 v5, s[0:1], v0, v0, 1.0
	v_rcp_f32_e32 v24, v5
	v_div_scale_f32 v25, vcc, 1.0, v0, 1.0
	v_fma_f32 v26, -v5, v24, 1.0
	v_fmac_f32_e32 v24, v26, v24
	v_mul_f32_e32 v26, v25, v24
	v_fma_f32 v27, -v5, v26, v25
	v_fmac_f32_e32 v26, v27, v24
	v_fma_f32 v5, -v5, v26, v25
	v_div_fmas_f32 v5, v5, v24, v26
	v_div_fixup_f32 v5, v5, v0, 1.0
	v_cmp_lt_f32_e32 vcc, 0, v0
	s_nop 1
	v_cndmask_b32_e32 v0, 0, v5, vcc
	v_cndmask_b32_e64 v5, 0, 1, s[12:13]
	v_pk_mul_f32 v[2:3], v[2:3], v[0:1] op_sel_hi:[1,0]
	v_pk_mul_f32 v[24:25], v[28:29], v[0:1] op_sel_hi:[1,0]
	v_pk_mul_f32 v[26:27], v[30:31], v[0:1] op_sel_hi:[1,0]
	v_pk_mul_f32 v[28:29], v[6:7], v[0:1] op_sel_hi:[1,0]
	v_pk_mul_f32 v[54:55], v[44:45], v[0:1] op_sel_hi:[1,0]
	v_pk_mul_f32 v[56:57], v[38:39], v[0:1] op_sel_hi:[1,0]
	v_pk_mul_f32 v[58:59], v[46:47], v[0:1] op_sel_hi:[1,0]
	v_pk_mul_f32 v[60:61], v[36:37], v[0:1] op_sel_hi:[1,0]
	v_pk_mul_f32 v[46:47], v[50:51], v[0:1] op_sel_hi:[1,0]
	v_pk_mul_f32 v[48:49], v[48:49], v[0:1] op_sel_hi:[1,0]
	v_pk_mul_f32 v[50:51], v[40:41], v[0:1] op_sel_hi:[1,0]
	v_pk_mul_f32 v[52:53], v[52:53], v[0:1] op_sel_hi:[1,0]
	v_pk_mul_f32 v[6:7], v[34:35], v[0:1] op_sel_hi:[1,0]
	v_pk_mul_f32 v[40:41], v[32:33], v[0:1] op_sel_hi:[1,0]
	v_pk_mul_f32 v[42:43], v[42:43], v[0:1] op_sel_hi:[1,0]
	v_cmp_ne_u32_e64 s[0:1], 1, v5
	s_andn2_b64 vcc, exec, s[12:13]
	v_pk_mul_f32 v[44:45], v[62:63], v[0:1] op_sel_hi:[1,0]
	s_cbranch_vccnz .LBB0_326
	ds_bpermute_b32 v84, v181, v3
	ds_bpermute_b32 v85, v181, v27
	ds_bpermute_b32 v86, v181, v55
	ds_bpermute_b32 v87, v181, v59
	ds_bpermute_b32 v88, v181, v47
	ds_bpermute_b32 v89, v181, v51
	ds_bpermute_b32 v90, v181, v7
	ds_bpermute_b32 v91, v181, v43
	ds_read2st64_b32 v[92:93], v155 offset0:88 offset1:89
	ds_read2st64_b32 v[94:95], v155 offset0:90 offset1:91
	ds_read2st64_b32 v[96:97], v155 offset0:92 offset1:93
	ds_read2st64_b32 v[98:99], v155 offset0:94 offset1:95
	s_waitcnt lgkmcnt(0)
	v_add_f32_e32 v5, v24, v25
	v_add_f32_e32 v5, v2, v5
	v_add_f32_e32 v32, v28, v29
	v_add_f32_e32 v32, v26, v32
	v_cndmask_b32_e64 v30, v84, 0, s[62:63]
	v_fmac_f32_e32 v30, 2.0, v5
	v_add_f32_e32 v5, v3, v30
	v_add_f32_e32 v5, v92, v5
	v_cndmask_b32_e64 v0, v85, v84, s[62:63]
	v_fmac_f32_e32 v0, 2.0, v32
	v_add_f32_e32 v0, v27, v0
	v_add_f32_e32 v0, v93, v0
	ds_write2st64_b32 v155, v5, v0 offset0:88 offset1:89
	v_add_f32_e32 v5, v56, v57
	v_add_f32_e32 v5, v54, v5
	v_add_f32_e32 v32, v60, v61
	v_add_f32_e32 v32, v58, v32
	v_cndmask_b32_e64 v30, v86, v85, s[62:63]
	v_fmac_f32_e32 v30, 2.0, v5
	v_add_f32_e32 v5, v55, v30
	v_add_f32_e32 v5, v94, v5
	v_cndmask_b32_e64 v0, v87, v86, s[62:63]
	v_fmac_f32_e32 v0, 2.0, v32
	v_add_f32_e32 v0, v59, v0
	v_add_f32_e32 v0, v95, v0
	ds_write2st64_b32 v155, v5, v0 offset0:90 offset1:91
	v_add_f32_e32 v5, v48, v49
	v_add_f32_e32 v5, v46, v5
	v_add_f32_e32 v32, v52, v53
	v_add_f32_e32 v32, v50, v32
	v_cndmask_b32_e64 v30, v88, v87, s[62:63]
	v_fmac_f32_e32 v30, 2.0, v5
	v_add_f32_e32 v5, v47, v30
	v_add_f32_e32 v5, v96, v5
	v_cndmask_b32_e64 v0, v89, v88, s[62:63]
	v_fmac_f32_e32 v0, 2.0, v32
	v_add_f32_e32 v0, v51, v0
	v_add_f32_e32 v0, v97, v0
	ds_write2st64_b32 v155, v5, v0 offset0:92 offset1:93
	v_add_f32_e32 v5, v40, v41
	v_add_f32_e32 v5, v6, v5
	v_add_f32_e32 v32, v44, v45
	v_add_f32_e32 v32, v42, v32
	v_cndmask_b32_e64 v30, v90, v89, s[62:63]
	v_fmac_f32_e32 v30, 2.0, v5
	v_add_f32_e32 v5, v7, v30
	v_add_f32_e32 v5, v98, v5
	v_cndmask_b32_e64 v0, v91, v90, s[62:63]
	v_fmac_f32_e32 v0, 2.0, v32
	v_add_f32_e32 v0, v43, v0
	v_add_f32_e32 v0, v99, v0
	ds_write2st64_b32 v155, v5, v0 offset0:94 offset1:95
